# conv item loop: static s_setprio 1 for waves 4-7 (desynchronise the two waves per SIMD so load and VALU stages overlap), reset at loop exit; on top of the GEMM static raise
# speedup vs baseline: 1.0112x; 1.0112x over previous
; #define LAS __attribute__((address_space(3)))
; DI bf16_t f2bf(float v) { return (bf16_t)(pk2(v, 0.f) & 0xffffu); }
; DI void conv_phase(PPtr p, int j, ldsp lds, int tid) {
;     ...
;     const int tok = tid >> 3, cgp = tid & 7;
;     for (int item = blockIdx.x; item < 256 * 12; item += gridDim.x) {
;         const int tt = item / 12, cb = item % 12;
;         const int t0 = tt * 64, b = t0 >> 12, s0 = t0 & 4095;
;         const int t = t0 + tok, s = s0 + tok;
;         u32x4 u[4][4];
; #pragma unroll
;         for (int k = 0; k < 4; ++k)
; #pragma unroll
;             for (int w = 0; w < 4; ++w) {
;                 const int ch0 = cb * 256 + (cgp + 8 * k) * 8;
;                 if (s - 3 + w >= 0) u[k][w] = *(const u32x4*)(zx + (size_t)(t - 3 + w) * ZXW + DIN + ch0);
;                 else u[k][w] = (u32x4){0u, 0u, 0u, 0u};
;             }
; #pragma unroll
;         for (int k = 0; k < 4; ++k) {
;             const int cl = (cgp + 8 * k) * 8, ch0 = cb * 256 + cl;
;     ...
;                 for (int i = 0; i < 8; ++i) *(LAS bf16_t*)(lds + (cl + i) * TPB + tok * 2) = f2bf(acc[i]);
;             }
;         }
;         if (cb < 10) {
;             __syncthreads();
; #pragma unroll
;             for (int k = 0; k < 4; ++k) { const int id = tid + 512 * k, row = id >> 3, ch = id & 7;
;                 const ldsp src = lds + row * TPB + ch * 16;
;                 u32x4 w; w.x = *(const LAS unsigned*)(src); w.y = *(const LAS unsigned*)(src + 4); w.z = *(const LAS unsigned*)(src + 8); w.w = *(const LAS unsigned*)(src + 12);
;                 bf16_t* dst = (cb < 8) ? xT + ((size_t)b * 2048 + cb * 256 + row) * SEQ + s0 + ch * 8 : BT + ((size_t)b * 512 + (cb - 8) * 256 + row) * SEQ + s0 + ch * 8;
.LBB0_510:
	v_readlane_b32 s0, v254, 13
	v_readlane_b32 s1, v254, 14
	s_andn2_b64 vcc, exec, s[0:1]
	s_cbranch_vccnz .LBB0_561
	v_readlane_b32 s0, v254, 51
	s_waitcnt lgkmcnt(0)
	s_add_u32 s2, s4, s0
	v_readlane_b32 s0, v254, 50
	s_addc_u32 s3, s5, s0
	v_readlane_b32 s0, v254, 53
	v_and_b32_e32 v2, 7, v42
	s_add_u32 s12, s6, s0
	v_readlane_b32 s0, v254, 52
	v_lshlrev_b32_e32 v72, 3, v2
	v_add_u32_e32 v7, 0x200, v42
	v_add_u32_e32 v8, 0x400, v42
	v_add_u32_e32 v9, 0x600, v42
	v_ashrrev_i32_e32 v70, 3, v42
	s_addc_u32 s13, s7, s0
	v_lshlrev_b32_e32 v0, 4, v2
	v_or_b32_e32 v5, 64, v72
	s_movk_i32 s0, 0x8c
	v_ashrrev_i32_e32 v74, 3, v7
	v_ashrrev_i32_e32 v76, 3, v8
	v_ashrrev_i32_e32 v78, 3, v9
	v_lshl_add_u32 v3, v70, 1, 0
	v_add_u32_e32 v4, 0, v0
	v_mul_u32_u24_e32 v2, 0x460, v2
	v_mul_u32_u24_e32 v5, 0x8c, v5
	v_mul_lo_u32 v6, v70, s0
	v_mul_lo_u32 v7, v74, s0
	v_mul_lo_u32 v8, v76, s0
	v_mul_lo_u32 v9, v78, s0
	v_mov_b32_e32 v73, v1
	v_ashrrev_i32_e32 v71, 31, v70
	v_ashrrev_i32_e32 v75, 31, v74
	v_ashrrev_i32_e32 v77, 31, v76
	v_ashrrev_i32_e32 v79, 31, v78
	v_lshl_add_u64 v[80:81], s[10:11], 0, v[0:1]
	s_lshl_b32 s18, s90, 8
	v_add_u32_e32 v84, v4, v6
	v_add_u32_e32 v85, v4, v7
	v_add_u32_e32 v86, v4, v8
	v_add_u32_e32 v87, v4, v9
	v_add_u32_e32 v88, v3, v2
	v_add_u32_e32 v89, v3, v5
	v_readlane_b32 s19, v254, 24
	v_readfirstlane_b32 s32, v153
	s_nop 3
	s_lshr_b32 s32, s32, 6
	s_cmp_ge_u32 s32, 4
	s_cbranch_scc0 .Lconv_prio_skip
	s_setprio 1
.Lconv_prio_skip:
	s_mov_b32 s20, s64
	s_cmpk_lg_u32 s90, 0x100
	s_cbranch_scc1 .LBB0_513
	s_mul_i32 s20, s64, 12
	s_lshl_b32 s19, s20, 8
	s_branch .LBB0_513

; #define LAS __attribute__((address_space(3)))
; DI unsigned xb_xcc_id() { return (unsigned)__builtin_amdgcn_s_getreg((3 << 11) | 20) & 0xFu; }
; DI void xcd_barrier(unsigned* bar_, volatile LAS unsigned* st_) {
;     XcdBarrier b; b.bar = bar_; b.st = st_; b.x = 0;
;     asm volatile("s_waitcnt vmcnt(0)" ::: "memory");
;     __syncthreads();
;     if (threadIdx.x == 0) {
;         unsigned* bar = b.bar; b.x = xb_xcc_id();
;         __builtin_amdgcn_s_waitcnt(0);
;         unsigned nloc = b.st[0], nx = b.st[1];
;         if (nloc == 0u) { xcd_barrier_complete(bar, b.x, nloc, nx); b.st[0] = nloc; b.st[1] = nx; }
.LBB0_561:
	s_setprio 0
	v_readlane_b32 s52, v255, 3
	v_readlane_b32 s53, v255, 4
	s_waitcnt vmcnt(0)
	s_waitcnt lgkmcnt(0)
	s_barrier
	s_and_saveexec_b64 s[0:1], s[66:67]
	s_cbranch_execz .LBB0_637
	v_readlane_b32 s5, v254, 28
	s_load_dwordx2 s[2:3], s[52:53], 0xc8
	s_getreg_b32 s4, hwreg(HW_REG_XCC_ID, 0, 4)
	v_mov_b32_e32 v0, s5
	s_waitcnt vmcnt(0) expcnt(0) lgkmcnt(0)
	ds_read_b32 v3, v0
	v_readlane_b32 s5, v254, 29
	s_and_b32 s18, s4, 15
	s_waitcnt lgkmcnt(0)
	v_cmp_ne_u32_e32 vcc, 0, v3
	v_mov_b32_e32 v0, s5
	ds_read_b32 v2, v0
	s_cbranch_vccnz .LBB0_577
	s_add_u32 s4, s2, 0x1000
	s_addc_u32 s5, s3, 0
	s_add_u32 s6, s2, 0x1100
	s_addc_u32 s7, s3, 0
	s_add_u32 s8, s2, 0x1200
	s_addc_u32 s9, s3, 0
	s_add_u32 s10, s2, 0x1300
	s_addc_u32 s11, s3, 0
	s_mov_b32 s19, 1
	s_branch .LBB0_565
